# v2 + hand-written attention compute section: pipelined K/V LDS reads, masks only on the two boundary tiles, dead tile skipped, exp2 fused scale (f32 softmax kept)
# speedup vs baseline: 1.0288x; 1.0076x over previous
; __device__ __forceinline__ f32x4 mfma16(bf16x8 a, bf16x8 b, f32x4 c) { return __builtin_amdgcn_mfma_f32_16x16x32_bf16(a, b, c, 0, 0, 0); }
; #define AT_LOADQ(T) do { const size_t tq_ = (T).tb + (size_t)(128 * (T).n + qi) * (T).d; \
;         _Pragma("unroll") for (int k4_ = 0; k4_ < 4; ++k4_) qf[k4_] = *(const bf16x8*)(AQ + tq_ * ATW + (T).head * 128 + k4_ * 32 + 8 * fq); qs = HS[tq_ * 24 + (T).head]; } while (0)
; __device__ __forceinline__ void attn_phase(int wv, const Args& a, LAS unsigned char* lds, int w, bool dmy) {
;     ...
;         bf16x8 qc[4];
; #pragma unroll
;         for (int k4 = 0; k4 < 4; ++k4) qc[k4] = qf[k4];
;         const float qscale = rsqrtf(qs * (1.f / 128.f) + EPS) * 0.08838834764831845f;
;         const size_t tokq = T.tb + (size_t)(128 * n + qi) * T.d;
;         __syncthreads();
;         if (it < 11) { T = attn_decode(12 * w + it + 1);
;             AT_LOADBLK(T, T.n); AT_LOADQ(T); }
;         const int px = (sl ^ 1) << 3;
;         const int lo2 = (wid & ~1) < 6 ? (wid & ~1) : 6;
;         f32x4 sT[10];
;         float mx = -INFINITY;
; #pragma unroll
;         for (int i = 0; i < 10; ++i) {
;             const int kt = lo2 + i, pkt = kt ^ px;
;             f32x4 ac = (f32x4){0.f, 0.f, 0.f, 0.f};
; #pragma unroll
;             for (int k4 = 0; k4 < 4; ++k4) ac = mfma16(lds_ld16(lds + AT_K + ((pkt * 16 + fr) * 136 + k4 * 32 + 8 * fq) * 2), qc[k4], ac);
; #pragma unroll
;             for (int rr = 0; rr < 4; ++rr) {
;                 const int ki = kt * 16 + 4 * fq + rr;
;                 const bool valid = (ki >= qi) && (ki <= qi + 128) && (n > 0 || ki >= 128);
;                 const float sv = valid ? ac[rr] * qscale : -INFINITY;
;                 ac[rr] = sv; mx = fmaxf(mx, sv);
;             }
;             sT[i] = ac;
;         }
.LBB0_657:
	v_rsq_f32_e32 v64, v64
	v_mov_b64_e32 v[66:67], s[86:87]
	v_lshl_add_u32 v65, s0, 7, v95
	v_mad_u64_u32 v[102:103], s[6:7], v65, s1, v[66:67]
	v_ashrrev_i32_e32 v68, 31, v65
	v_mov_b32_e32 v66, v103
	v_mad_u64_u32 v[100:101], s[6:7], v68, s1, v[66:67]
	v_mul_f32_e32 v65, 0x45800000, v64
	v_readfirstlane_b32 s3, v95
	v_cndmask_b32_e32 v64, v64, v65, vcc
	s_lshr_b32 s3, s3, 4
	s_lshl_b32 s1, s2, 3
	s_xor_b32 s1, s1, 8
	s_add_u32 s1, s1, s3
	s_movk_i32 s9, 0x110
	v_mad_u32_u24 v83, v85, s9, v96
	v_add_u32_e32 v82, v106, v88
	v_lshl_add_u32 v82, v82, 1, s94
	v_sub_u32_e32 v80, v88, v85
	v_mul_f32_e32 v64, 0x3db504f3, v64
	s_add_u32 s6, s1, 0
	s_and_b32 s6, s6, 15
	s_mul_i32 s7, s6, 0x1100
	s_lshl_b32 s6, s6, 5
	v_add_u32_e32 v68, s7, v83
	v_add_u32_e32 v182, s6, v82
	s_add_u32 s6, s1, 1
	s_and_b32 s6, s6, 15
	s_mul_i32 s7, s6, 0x1100
	s_lshl_b32 s6, s6, 5
	v_add_u32_e32 v69, s7, v83
	v_add_u32_e32 v183, s6, v82
	s_add_u32 s6, s1, 2
	s_and_b32 s6, s6, 15
	s_mul_i32 s7, s6, 0x1100
	s_lshl_b32 s6, s6, 5
	v_add_u32_e32 v70, s7, v83
	v_add_u32_e32 v184, s6, v82
	s_add_u32 s6, s1, 3
	s_and_b32 s6, s6, 15
	s_mul_i32 s7, s6, 0x1100
	s_lshl_b32 s6, s6, 5
	v_add_u32_e32 v71, s7, v83
	v_add_u32_e32 v185, s6, v82
	s_add_u32 s6, s1, 4
	s_and_b32 s6, s6, 15
	s_mul_i32 s7, s6, 0x1100
	s_lshl_b32 s6, s6, 5
	v_add_u32_e32 v72, s7, v83
	v_add_u32_e32 v186, s6, v82
	s_add_u32 s6, s1, 5
	s_and_b32 s6, s6, 15
	s_mul_i32 s7, s6, 0x1100
	s_lshl_b32 s6, s6, 5
	v_add_u32_e32 v73, s7, v83
	v_add_u32_e32 v187, s6, v82
	s_add_u32 s6, s1, 6
	s_and_b32 s6, s6, 15
	s_mul_i32 s7, s6, 0x1100
	s_lshl_b32 s6, s6, 5
	v_add_u32_e32 v74, s7, v83
	v_add_u32_e32 v227, s6, v82
	s_add_u32 s6, s1, 7
	s_and_b32 s6, s6, 15
	s_mul_i32 s7, s6, 0x1100
	s_lshl_b32 s6, s6, 5
	v_add_u32_e32 v75, s7, v83
	v_add_u32_e32 v228, s6, v82
	s_add_u32 s6, s1, 8
	s_and_b32 s6, s6, 15
	s_mul_i32 s7, s6, 0x1100
	s_lshl_b32 s6, s6, 5
	v_add_u32_e32 v76, s7, v83
	v_add_u32_e32 v234, s6, v82
	ds_read_b128 v[166:169], v68
	ds_read_b128 v[170:173], v68 offset:64
	ds_read_b128 v[174:177], v68 offset:128
	ds_read_b128 v[178:181], v68 offset:192
	ds_read_b128 v[198:201], v69
	ds_read_b128 v[202:205], v69 offset:64
	ds_read_b128 v[206:209], v69 offset:128
	ds_read_b128 v[210:213], v69 offset:192
	s_waitcnt lgkmcnt(7)
	v_mfma_f32_16x16x32_bf16 v[124:127], v[166:169], v[60:63], 0
	s_waitcnt lgkmcnt(6)
	v_mfma_f32_16x16x32_bf16 v[124:127], v[170:173], v[56:59], v[124:127]
	s_waitcnt lgkmcnt(5)
	v_mfma_f32_16x16x32_bf16 v[124:127], v[174:177], v[52:55], v[124:127]
	s_waitcnt lgkmcnt(4)
	v_mfma_f32_16x16x32_bf16 v[124:127], v[178:181], v[48:51], v[124:127]
	ds_read_b128 v[166:169], v70
	ds_read_b128 v[170:173], v70 offset:64
	ds_read_b128 v[174:177], v70 offset:128
	ds_read_b128 v[178:181], v70 offset:192
	s_waitcnt lgkmcnt(7)
	v_mfma_f32_16x16x32_bf16 v[128:131], v[198:201], v[60:63], 0
	s_waitcnt lgkmcnt(6)
	v_mfma_f32_16x16x32_bf16 v[128:131], v[202:205], v[56:59], v[128:131]
	s_waitcnt lgkmcnt(5)
	v_mfma_f32_16x16x32_bf16 v[128:131], v[206:209], v[52:55], v[128:131]
	s_waitcnt lgkmcnt(4)
	v_mfma_f32_16x16x32_bf16 v[128:131], v[210:213], v[48:51], v[128:131]
	ds_read_b128 v[198:201], v71
	ds_read_b128 v[202:205], v71 offset:64
	ds_read_b128 v[206:209], v71 offset:128
	ds_read_b128 v[210:213], v71 offset:192
	s_waitcnt lgkmcnt(7)
	v_mfma_f32_16x16x32_bf16 v[132:135], v[166:169], v[60:63], 0
	s_waitcnt lgkmcnt(6)
	v_mfma_f32_16x16x32_bf16 v[132:135], v[170:173], v[56:59], v[132:135]
	s_waitcnt lgkmcnt(5)
	v_mfma_f32_16x16x32_bf16 v[132:135], v[174:177], v[52:55], v[132:135]
	s_waitcnt lgkmcnt(4)
	v_mfma_f32_16x16x32_bf16 v[132:135], v[178:181], v[48:51], v[132:135]
	ds_read_b128 v[166:169], v72
	ds_read_b128 v[170:173], v72 offset:64
	ds_read_b128 v[174:177], v72 offset:128
	ds_read_b128 v[178:181], v72 offset:192
	s_waitcnt lgkmcnt(7)
	v_mfma_f32_16x16x32_bf16 v[136:139], v[198:201], v[60:63], 0
	s_waitcnt lgkmcnt(6)
	v_mfma_f32_16x16x32_bf16 v[136:139], v[202:205], v[56:59], v[136:139]
	s_waitcnt lgkmcnt(5)
	v_mfma_f32_16x16x32_bf16 v[136:139], v[206:209], v[52:55], v[136:139]
	s_waitcnt lgkmcnt(4)
	v_mfma_f32_16x16x32_bf16 v[136:139], v[210:213], v[48:51], v[136:139]
	ds_read_b128 v[198:201], v73
	ds_read_b128 v[202:205], v73 offset:64
	ds_read_b128 v[206:209], v73 offset:128
	ds_read_b128 v[210:213], v73 offset:192
	s_waitcnt lgkmcnt(7)
	v_mfma_f32_16x16x32_bf16 v[140:143], v[166:169], v[60:63], 0
	s_waitcnt lgkmcnt(6)
	v_mfma_f32_16x16x32_bf16 v[140:143], v[170:173], v[56:59], v[140:143]
	s_waitcnt lgkmcnt(5)
	v_mfma_f32_16x16x32_bf16 v[140:143], v[174:177], v[52:55], v[140:143]
	s_waitcnt lgkmcnt(4)
	v_mfma_f32_16x16x32_bf16 v[140:143], v[178:181], v[48:51], v[140:143]
	ds_read_b128 v[166:169], v74
	ds_read_b128 v[170:173], v74 offset:64
	ds_read_b128 v[174:177], v74 offset:128
	ds_read_b128 v[178:181], v74 offset:192
	s_waitcnt lgkmcnt(7)
	v_mfma_f32_16x16x32_bf16 v[144:147], v[198:201], v[60:63], 0
	s_waitcnt lgkmcnt(6)
	v_mfma_f32_16x16x32_bf16 v[144:147], v[202:205], v[56:59], v[144:147]
	s_waitcnt lgkmcnt(5)
	v_mfma_f32_16x16x32_bf16 v[144:147], v[206:209], v[52:55], v[144:147]
	s_waitcnt lgkmcnt(4)
	v_mfma_f32_16x16x32_bf16 v[144:147], v[210:213], v[48:51], v[144:147]
	ds_read_b128 v[198:201], v75
	ds_read_b128 v[202:205], v75 offset:64
	ds_read_b128 v[206:209], v75 offset:128
	ds_read_b128 v[210:213], v75 offset:192
	s_waitcnt lgkmcnt(7)
	v_mfma_f32_16x16x32_bf16 v[148:151], v[166:169], v[60:63], 0
	s_waitcnt lgkmcnt(6)
	v_mfma_f32_16x16x32_bf16 v[148:151], v[170:173], v[56:59], v[148:151]
	s_waitcnt lgkmcnt(5)
	v_mfma_f32_16x16x32_bf16 v[148:151], v[174:177], v[52:55], v[148:151]
	s_waitcnt lgkmcnt(4)
; __device__ __forceinline__ float shx(float v, int lane, int mask) { return __int_as_float(__builtin_amdgcn_ds_bpermute((lane ^ mask) << 2, __float_as_int(v))); }
; __device__ __forceinline__ f32x4 mfma16(bf16x8 a, bf16x8 b, f32x4 c) { return __builtin_amdgcn_mfma_f32_16x16x32_bf16(a, b, c, 0, 0, 0); }
; __device__ __forceinline__ void attn_phase(int wv, const Args& a, LAS unsigned char* lds, int w, bool dmy) {
;     ...
;         for (int i = 0; i < 10; ++i) {
;             const int kt = lo2 + i, pkt = kt ^ px;
;             f32x4 ac = (f32x4){0.f, 0.f, 0.f, 0.f};
; #pragma unroll
;             for (int k4 = 0; k4 < 4; ++k4) ac = mfma16(lds_ld16(lds + AT_K + ((pkt * 16 + fr) * 136 + k4 * 32 + 8 * fq) * 2), qc[k4], ac);
; #pragma unroll
;             for (int rr = 0; rr < 4; ++rr) {
;                 const int ki = kt * 16 + 4 * fq + rr;
;                 const bool valid = (ki >= qi) && (ki <= qi + 128) && (n > 0 || ki >= 128);
;                 const float sv = valid ? ac[rr] * qscale : -INFINITY;
;                 ac[rr] = sv; mx = fmaxf(mx, sv);
;             }
;             sT[i] = ac;
;         }
;         mx = fmaxf(mx, shx(mx, LANE_, 16)); mx = fmaxf(mx, shx(mx, LANE_, 32));
;         float sum = 0.f;
; #pragma unroll
;         for (int i = 0; i < 10; ++i)
; #pragma unroll
;             for (int rr = 0; rr < 4; ++rr) { const float pv = __expf(sT[i][rr] - mx); sT[i][rr] = pv; sum += pv; }
;         sum += shx(sum, LANE_, 16); sum += shx(sum, LANE_, 32);
	v_mfma_f32_16x16x32_bf16 v[148:151], v[178:181], v[48:51], v[148:151]
	ds_read_b128 v[166:169], v76
	ds_read_b128 v[170:173], v76 offset:64
	ds_read_b128 v[174:177], v76 offset:128
	ds_read_b128 v[178:181], v76 offset:192
	s_waitcnt lgkmcnt(7)
	v_mfma_f32_16x16x32_bf16 v[152:155], v[198:201], v[60:63], 0
	s_waitcnt lgkmcnt(6)
	v_mfma_f32_16x16x32_bf16 v[152:155], v[202:205], v[56:59], v[152:155]
	s_waitcnt lgkmcnt(5)
	v_mfma_f32_16x16x32_bf16 v[152:155], v[206:209], v[52:55], v[152:155]
	s_waitcnt lgkmcnt(4)
	v_mfma_f32_16x16x32_bf16 v[152:155], v[210:213], v[48:51], v[152:155]
	s_waitcnt lgkmcnt(3)
	v_mfma_f32_16x16x32_bf16 v[156:159], v[166:169], v[60:63], 0
	s_waitcnt lgkmcnt(2)
	v_mfma_f32_16x16x32_bf16 v[156:159], v[170:173], v[56:59], v[156:159]
	s_waitcnt lgkmcnt(1)
	v_mfma_f32_16x16x32_bf16 v[156:159], v[174:177], v[52:55], v[156:159]
	s_waitcnt lgkmcnt(0)
	v_mfma_f32_16x16x32_bf16 v[156:159], v[178:181], v[48:51], v[156:159]
	v_mov_b32_e32 v66, v64
	v_mul_f32_e32 v64, 0x3fb8aa3b, v64
	v_cmp_le_i32_e64 s[88:89], 0, v80
	v_cmp_le_i32_e64 s[90:91], -1, v80
	v_cmp_le_i32_e64 s[2:3], -2, v80
	v_cmp_le_i32_e64 s[6:7], -3, v80
	v_cndmask_b32_e64 v124, v238, v124, s[88:89]
	v_cndmask_b32_e64 v125, v238, v125, s[90:91]
	v_cndmask_b32_e64 v126, v238, v126, s[2:3]
	v_cndmask_b32_e64 v127, v238, v127, s[6:7]
	v_cmp_ge_i32_e64 s[88:89], 0, v80
	v_cmp_ge_i32_e64 s[90:91], -1, v80
	v_cmp_ge_i32_e64 s[2:3], -2, v80
	v_cmp_ge_i32_e64 s[6:7], -3, v80
	s_nop 3
	v_cndmask_b32_e64 v156, v238, v156, s[88:89]
	v_cndmask_b32_e64 v157, v238, v157, s[90:91]
	v_cndmask_b32_e64 v158, v238, v158, s[2:3]
	v_cndmask_b32_e64 v159, v238, v159, s[6:7]
	s_cmp_lg_u32 s0, 0
	s_cbranch_scc1 .Lat_n_ok
	v_readfirstlane_b32 s3, v95
	s_lshr_b32 s3, s3, 4
	s_add_u32 s6, s3, 0
	s_cmp_lt_u32 s6, 8
	s_cbranch_scc0 .Lat_n_ok
	v_mov_b32_e32 v124, v238
	v_mov_b32_e32 v125, v238
	v_mov_b32_e32 v126, v238
	v_mov_b32_e32 v127, v238
	s_add_u32 s6, s3, 1
	s_cmp_lt_u32 s6, 8
	s_cbranch_scc0 .Lat_n_ok
	v_mov_b32_e32 v128, v238
	v_mov_b32_e32 v129, v238
	v_mov_b32_e32 v130, v238
	v_mov_b32_e32 v131, v238
	s_add_u32 s6, s3, 2
	s_cmp_lt_u32 s6, 8
	s_cbranch_scc0 .Lat_n_ok
	v_mov_b32_e32 v132, v238
	v_mov_b32_e32 v133, v238
	v_mov_b32_e32 v134, v238
	v_mov_b32_e32 v135, v238
	s_add_u32 s6, s3, 3
	s_cmp_lt_u32 s6, 8
	s_cbranch_scc0 .Lat_n_ok
	v_mov_b32_e32 v136, v238
	v_mov_b32_e32 v137, v238
	v_mov_b32_e32 v138, v238
	v_mov_b32_e32 v139, v238
	s_add_u32 s6, s3, 4
	s_cmp_lt_u32 s6, 8
	s_cbranch_scc0 .Lat_n_ok
	v_mov_b32_e32 v140, v238
	v_mov_b32_e32 v141, v238
	v_mov_b32_e32 v142, v238
	v_mov_b32_e32 v143, v238
	s_add_u32 s6, s3, 5
	s_cmp_lt_u32 s6, 8
	s_cbranch_scc0 .Lat_n_ok
	v_mov_b32_e32 v144, v238
	v_mov_b32_e32 v145, v238
	v_mov_b32_e32 v146, v238
	v_mov_b32_e32 v147, v238
	s_add_u32 s6, s3, 6
	s_cmp_lt_u32 s6, 8
	s_cbranch_scc0 .Lat_n_ok
	v_mov_b32_e32 v148, v238
	v_mov_b32_e32 v149, v238
	v_mov_b32_e32 v150, v238
	v_mov_b32_e32 v151, v238
	s_add_u32 s6, s3, 7
	s_cmp_lt_u32 s6, 8
	s_cbranch_scc0 .Lat_n_ok
	v_mov_b32_e32 v152, v238
	v_mov_b32_e32 v153, v238
	v_mov_b32_e32 v154, v238
	v_mov_b32_e32 v155, v238
.Lat_n_ok:
	v_max3_f32 v65, v124, v125, v126
	v_max3_f32 v65, v65, v127, v128
	v_max3_f32 v65, v65, v129, v130
	v_max3_f32 v65, v65, v131, v132
	v_max3_f32 v65, v65, v133, v134
	v_max3_f32 v65, v65, v135, v136
	v_max3_f32 v65, v65, v137, v138
	v_max3_f32 v65, v65, v139, v140
	v_max3_f32 v65, v65, v141, v142
	v_max3_f32 v65, v65, v143, v144
	v_max3_f32 v65, v65, v145, v146
	v_max3_f32 v65, v65, v147, v148
	v_max3_f32 v65, v65, v149, v150
	v_max3_f32 v65, v65, v151, v152
	v_max3_f32 v65, v65, v153, v154
	v_max3_f32 v65, v65, v155, v156
	v_max3_f32 v65, v65, v157, v158
	v_max_f32_e32 v65, v65, v159
	ds_bpermute_b32 v67, v97, v65
	s_waitcnt lgkmcnt(0)
	v_max_f32_e32 v65, v65, v67
	ds_bpermute_b32 v67, v104, v65
	s_waitcnt lgkmcnt(0)
	v_max_f32_e32 v65, v65, v67
	v_mul_f32_e32 v101, v65, v66
	v_mul_f32_e32 v65, v65, v64
	v_fma_f32 v124, v124, v64, -v65
	v_fma_f32 v125, v125, v64, -v65
	v_fma_f32 v126, v126, v64, -v65
	v_fma_f32 v127, v127, v64, -v65
	v_fma_f32 v128, v128, v64, -v65
	v_fma_f32 v129, v129, v64, -v65
	v_fma_f32 v130, v130, v64, -v65
	v_fma_f32 v131, v131, v64, -v65
	v_fma_f32 v132, v132, v64, -v65
	v_fma_f32 v133, v133, v64, -v65
	v_fma_f32 v134, v134, v64, -v65
	v_fma_f32 v135, v135, v64, -v65
	v_fma_f32 v136, v136, v64, -v65
	v_fma_f32 v137, v137, v64, -v65
	v_fma_f32 v138, v138, v64, -v65
	v_fma_f32 v139, v139, v64, -v65
	v_fma_f32 v140, v140, v64, -v65
	v_fma_f32 v141, v141, v64, -v65
	v_fma_f32 v142, v142, v64, -v65
	v_fma_f32 v143, v143, v64, -v65
	v_fma_f32 v144, v144, v64, -v65
	v_fma_f32 v145, v145, v64, -v65
	v_fma_f32 v146, v146, v64, -v65
	v_fma_f32 v147, v147, v64, -v65
	v_fma_f32 v148, v148, v64, -v65
	v_fma_f32 v149, v149, v64, -v65
	v_fma_f32 v150, v150, v64, -v65
	v_fma_f32 v151, v151, v64, -v65
	v_fma_f32 v152, v152, v64, -v65
	v_fma_f32 v153, v153, v64, -v65
	v_fma_f32 v154, v154, v64, -v65
	v_fma_f32 v155, v155, v64, -v65
	v_fma_f32 v156, v156, v64, -v65
	v_fma_f32 v157, v157, v64, -v65
	v_fma_f32 v158, v158, v64, -v65
	v_fma_f32 v159, v159, v64, -v65
	v_exp_f32_e32 v124, v124
	v_exp_f32_e32 v125, v125
	v_exp_f32_e32 v126, v126
	v_add_f32_e32 v103, v124, v125
	v_exp_f32_e32 v127, v127
	v_add_f32_e32 v103, v103, v126
	v_exp_f32_e32 v128, v128
	v_add_f32_e32 v103, v103, v127
	v_exp_f32_e32 v129, v129
	v_add_f32_e32 v103, v103, v128
	v_exp_f32_e32 v130, v130
	v_add_f32_e32 v103, v103, v129
	v_exp_f32_e32 v131, v131
	v_add_f32_e32 v103, v103, v130
	v_exp_f32_e32 v132, v132
	v_add_f32_e32 v103, v103, v131
	v_exp_f32_e32 v133, v133
	v_add_f32_e32 v103, v103, v132
; #define LAS __attribute__((address_space(3)))
; __device__ __forceinline__ unsigned pk2(float lo, float hi) { f32x2 v = {lo, hi}; bf2_t b = __builtin_convertvector(v, bf2_t); return __builtin_bit_cast(unsigned, b); }
; __device__ __forceinline__ float shx(float v, int lane, int mask) { return __int_as_float(__builtin_amdgcn_ds_bpermute((lane ^ mask) << 2, __float_as_int(v))); }
; __device__ __forceinline__ f32x4 mfma16(bf16x8 a, bf16x8 b, f32x4 c) { return __builtin_amdgcn_mfma_f32_16x16x32_bf16(a, b, c, 0, 0, 0); }
; __device__ __forceinline__ void attn_phase(int wv, const Args& a, LAS unsigned char* lds, int w, bool dmy) {
;     ...
;         float sum = 0.f;
; #pragma unroll
;         for (int i = 0; i < 10; ++i)
; #pragma unroll
;             for (int rr = 0; rr < 4; ++rr) { const float pv = __expf(sT[i][rr] - mx); sT[i][rr] = pv; sum += pv; }
;         sum += shx(sum, LANE_, 16); sum += shx(sum, LANE_, 32);
;         f32x4 oacc[8];
; #pragma unroll
;         for (int j = 0; j < 8; ++j) oacc[j] = (f32x4){0.f, 0.f, 0.f, 0.f};
; #pragma unroll
;         for (int pp = 0; pp < 5; ++pp) {
;             const int pk0 = (lo2 + 2 * pp) ^ px, pk1 = (lo2 + 2 * pp + 1) ^ px;
;             u32x4 pw; pw.x = pk2(sT[2 * pp][0], sT[2 * pp][1]); pw.y = pk2(sT[2 * pp][2], sT[2 * pp][3]); pw.z = pk2(sT[2 * pp + 1][0], sT[2 * pp + 1][1]); pw.w = pk2(sT[2 * pp + 1][2], sT[2 * pp + 1][3]);
;             const bf16x8 pf = __builtin_bit_cast(bf16x8, pw);
; #pragma unroll
;             for (int j = 0; j < 8; ++j) {
;                 const u32x2 v0 = *(const LAS u32x2*)(lds + AT_V + ((j * 16 + fr) * 264 + pk0 * 16 + 4 * fq) * 2);
;                 const u32x2 v1 = *(const LAS u32x2*)(lds + AT_V + ((j * 16 + fr) * 264 + pk1 * 16 + 4 * fq) * 2);
;                 const u32x4 vw = (u32x4){v0.x, v0.y, v1.x, v1.y};
;                 oacc[j] = mfma16(__builtin_bit_cast(bf16x8, vw), pf, oacc[j]);
;             }
;         }
	v_exp_f32_e32 v134, v134
	v_add_f32_e32 v103, v103, v133
	v_exp_f32_e32 v135, v135
	v_add_f32_e32 v103, v103, v134
	v_exp_f32_e32 v136, v136
	v_add_f32_e32 v103, v103, v135
	v_exp_f32_e32 v137, v137
	v_add_f32_e32 v103, v103, v136
	v_exp_f32_e32 v138, v138
	v_add_f32_e32 v103, v103, v137
	v_exp_f32_e32 v139, v139
	v_add_f32_e32 v103, v103, v138
	v_exp_f32_e32 v140, v140
	v_add_f32_e32 v103, v103, v139
	v_exp_f32_e32 v141, v141
	v_add_f32_e32 v103, v103, v140
	v_exp_f32_e32 v142, v142
	v_add_f32_e32 v103, v103, v141
	v_exp_f32_e32 v143, v143
	v_add_f32_e32 v103, v103, v142
	v_exp_f32_e32 v144, v144
	v_add_f32_e32 v103, v103, v143
	v_exp_f32_e32 v145, v145
	v_add_f32_e32 v103, v103, v144
	v_exp_f32_e32 v146, v146
	v_add_f32_e32 v103, v103, v145
	v_exp_f32_e32 v147, v147
	v_add_f32_e32 v103, v103, v146
	v_exp_f32_e32 v148, v148
	v_add_f32_e32 v103, v103, v147
	v_exp_f32_e32 v149, v149
	v_add_f32_e32 v103, v103, v148
	v_exp_f32_e32 v150, v150
	v_add_f32_e32 v103, v103, v149
	v_exp_f32_e32 v151, v151
	v_add_f32_e32 v103, v103, v150
	v_exp_f32_e32 v152, v152
	v_add_f32_e32 v103, v103, v151
	v_exp_f32_e32 v153, v153
	v_add_f32_e32 v103, v103, v152
	v_exp_f32_e32 v154, v154
	v_add_f32_e32 v103, v103, v153
	v_exp_f32_e32 v155, v155
	v_add_f32_e32 v103, v103, v154
	v_exp_f32_e32 v156, v156
	v_add_f32_e32 v103, v103, v155
	v_exp_f32_e32 v157, v157
	v_add_f32_e32 v103, v103, v156
	v_exp_f32_e32 v158, v158
	v_add_f32_e32 v103, v103, v157
	v_exp_f32_e32 v159, v159
	v_add_f32_e32 v103, v103, v158
	s_nop 0
	v_add_f32_e32 v103, v103, v159
	ds_bpermute_b32 v67, v97, v103
	v_cvt_pk_bf16_f32 v166, v124, v125
	v_cvt_pk_bf16_f32 v167, v126, v127
	v_cvt_pk_bf16_f32 v168, v128, v129
	v_cvt_pk_bf16_f32 v169, v130, v131
	v_cvt_pk_bf16_f32 v170, v132, v133
	v_cvt_pk_bf16_f32 v171, v134, v135
	v_cvt_pk_bf16_f32 v172, v136, v137
	v_cvt_pk_bf16_f32 v173, v138, v139
	v_cvt_pk_bf16_f32 v174, v140, v141
	v_cvt_pk_bf16_f32 v175, v142, v143
	v_cvt_pk_bf16_f32 v176, v144, v145
	v_cvt_pk_bf16_f32 v177, v146, v147
	v_cvt_pk_bf16_f32 v178, v148, v149
	v_cvt_pk_bf16_f32 v179, v150, v151
	v_cvt_pk_bf16_f32 v180, v152, v153
	v_cvt_pk_bf16_f32 v181, v154, v155
	v_cvt_pk_bf16_f32 v198, v156, v157
	v_cvt_pk_bf16_f32 v199, v158, v159
	v_mov_b32_e32 v200, 0
	v_mov_b32_e32 v201, 0
	s_waitcnt lgkmcnt(0)
	v_add_f32_e32 v103, v103, v67
	ds_bpermute_b32 v67, v104, v103
	s_waitcnt lgkmcnt(0)
	v_add_f32_e32 v81, v103, v67
	ds_read_b64 v[48:49], v182
	ds_read_b64 v[50:51], v183
	ds_read_b64 v[52:53], v182 offset:8448
	ds_read_b64 v[54:55], v183 offset:8448
	ds_read_b64 v[56:57], v182 offset:16896
	ds_read_b64 v[58:59], v183 offset:16896
	ds_read_b64 v[60:61], v182 offset:25344
	ds_read_b64 v[62:63], v183 offset:25344
	ds_read_b64 v[64:65], v182 offset:33792
	ds_read_b64 v[66:67], v183 offset:33792
	ds_read_b64 v[68:69], v182 offset:42240
	ds_read_b64 v[70:71], v183 offset:42240
	ds_read_b64 v[72:73], v182 offset:50688
	ds_read_b64 v[74:75], v183 offset:50688
	ds_read_b64 v[76:77], v182 offset:59136
	s_waitcnt lgkmcnt(14)
	ds_read_b64 v[78:79], v183 offset:59136
	s_waitcnt lgkmcnt(8)
	v_mfma_f32_16x16x32_bf16 v[124:127], v[48:51], v[166:169], 0
	v_mfma_f32_16x16x32_bf16 v[128:131], v[52:55], v[166:169], 0
	v_mfma_f32_16x16x32_bf16 v[132:135], v[56:59], v[166:169], 0
	v_mfma_f32_16x16x32_bf16 v[136:139], v[60:63], v[166:169], 0
	ds_read_b64 v[48:49], v184
	ds_read_b64 v[50:51], v185
	ds_read_b64 v[52:53], v184 offset:8448
	ds_read_b64 v[54:55], v185 offset:8448
	ds_read_b64 v[56:57], v184 offset:16896
	ds_read_b64 v[58:59], v185 offset:16896
	ds_read_b64 v[60:61], v184 offset:25344
	s_waitcnt lgkmcnt(14)
	ds_read_b64 v[62:63], v185 offset:25344
	s_waitcnt lgkmcnt(8)
	v_mfma_f32_16x16x32_bf16 v[140:143], v[64:67], v[166:169], 0
	v_mfma_f32_16x16x32_bf16 v[144:147], v[68:71], v[166:169], 0
	v_mfma_f32_16x16x32_bf16 v[148:151], v[72:75], v[166:169], 0
	v_mfma_f32_16x16x32_bf16 v[152:155], v[76:79], v[166:169], 0
	ds_read_b64 v[64:65], v184 offset:33792
	ds_read_b64 v[66:67], v185 offset:33792
	ds_read_b64 v[68:69], v184 offset:42240
	ds_read_b64 v[70:71], v185 offset:42240
	ds_read_b64 v[72:73], v184 offset:50688
	ds_read_b64 v[74:75], v185 offset:50688
	ds_read_b64 v[76:77], v184 offset:59136
	s_waitcnt lgkmcnt(14)
	ds_read_b64 v[78:79], v185 offset:59136
	s_waitcnt lgkmcnt(8)
	v_mfma_f32_16x16x32_bf16 v[124:127], v[48:51], v[170:173], v[124:127]
	v_mfma_f32_16x16x32_bf16 v[128:131], v[52:55], v[170:173], v[128:131]
	v_mfma_f32_16x16x32_bf16 v[132:135], v[56:59], v[170:173], v[132:135]
	v_mfma_f32_16x16x32_bf16 v[136:139], v[60:63], v[170:173], v[136:139]
	ds_read_b64 v[48:49], v186
	ds_read_b64 v[50:51], v187
	ds_read_b64 v[52:53], v186 offset:8448
	ds_read_b64 v[54:55], v187 offset:8448
	ds_read_b64 v[56:57], v186 offset:16896
	ds_read_b64 v[58:59], v187 offset:16896
	ds_read_b64 v[60:61], v186 offset:25344
	s_waitcnt lgkmcnt(14)
	ds_read_b64 v[62:63], v187 offset:25344
	s_waitcnt lgkmcnt(8)
	v_mfma_f32_16x16x32_bf16 v[140:143], v[64:67], v[170:173], v[140:143]
	v_mfma_f32_16x16x32_bf16 v[144:147], v[68:71], v[170:173], v[144:147]
	v_mfma_f32_16x16x32_bf16 v[148:151], v[72:75], v[170:173], v[148:151]
	v_mfma_f32_16x16x32_bf16 v[152:155], v[76:79], v[170:173], v[152:155]
	ds_read_b64 v[64:65], v186 offset:33792
	ds_read_b64 v[66:67], v187 offset:33792
	ds_read_b64 v[68:69], v186 offset:42240
	ds_read_b64 v[70:71], v187 offset:42240
	ds_read_b64 v[72:73], v186 offset:50688
	ds_read_b64 v[74:75], v187 offset:50688
	ds_read_b64 v[76:77], v186 offset:59136
	s_waitcnt lgkmcnt(14)
	ds_read_b64 v[78:79], v187 offset:59136
	s_waitcnt lgkmcnt(8)
; #define LAS __attribute__((address_space(3)))
; __device__ __forceinline__ unsigned pk2(float lo, float hi) { f32x2 v = {lo, hi}; bf2_t b = __builtin_convertvector(v, bf2_t); return __builtin_bit_cast(unsigned, b); }
; __device__ __forceinline__ f32x4 mfma16(bf16x8 a, bf16x8 b, f32x4 c) { return __builtin_amdgcn_mfma_f32_16x16x32_bf16(a, b, c, 0, 0, 0); }
; __device__ __forceinline__ void attn_phase(int wv, const Args& a, LAS unsigned char* lds, int w, bool dmy) {
;     ...
; #pragma unroll
;         for (int pp = 0; pp < 5; ++pp) {
;             const int pk0 = (lo2 + 2 * pp) ^ px, pk1 = (lo2 + 2 * pp + 1) ^ px;
;             u32x4 pw; pw.x = pk2(sT[2 * pp][0], sT[2 * pp][1]); pw.y = pk2(sT[2 * pp][2], sT[2 * pp][3]); pw.z = pk2(sT[2 * pp + 1][0], sT[2 * pp + 1][1]); pw.w = pk2(sT[2 * pp + 1][2], sT[2 * pp + 1][3]);
;             const bf16x8 pf = __builtin_bit_cast(bf16x8, pw);
; #pragma unroll
;             for (int j = 0; j < 8; ++j) {
;                 const u32x2 v0 = *(const LAS u32x2*)(lds + AT_V + ((j * 16 + fr) * 264 + pk0 * 16 + 4 * fq) * 2);
;                 const u32x2 v1 = *(const LAS u32x2*)(lds + AT_V + ((j * 16 + fr) * 264 + pk1 * 16 + 4 * fq) * 2);
;                 const u32x4 vw = (u32x4){v0.x, v0.y, v1.x, v1.y};
;                 oacc[j] = mfma16(__builtin_bit_cast(bf16x8, vw), pf, oacc[j]);
;             }
;         }
;         const float inv = 1.f / sum;
; #pragma unroll
;         for (int j = 0; j < 8; ++j) { u32x2 wv; wv.x = pk2(oacc[j][0] * inv, oacc[j][1] * inv); wv.y = pk2(oacc[j][2] * inv, oacc[j][3] * inv);
;             *(u32x2*)((dmy ? (bf16_t*)(a.ws + WS_DUMMY) + (size_t)qi * ATW : AQ + tokq * ATW) + head * 128 + j * 16 + 4 * fq) = wv; }
;         if (fq == 0) (dmy ? (float*)(a.ws + WS_DUMMY + MiB) + qi * 12 : LSE + tokq * 12)[head] = mx + __logf(sum);
	v_mfma_f32_16x16x32_bf16 v[124:127], v[48:51], v[174:177], v[124:127]
	v_mfma_f32_16x16x32_bf16 v[128:131], v[52:55], v[174:177], v[128:131]
	v_mfma_f32_16x16x32_bf16 v[132:135], v[56:59], v[174:177], v[132:135]
	v_mfma_f32_16x16x32_bf16 v[136:139], v[60:63], v[174:177], v[136:139]
	ds_read_b64 v[48:49], v227
	ds_read_b64 v[50:51], v228
	ds_read_b64 v[52:53], v227 offset:8448
	ds_read_b64 v[54:55], v228 offset:8448
	ds_read_b64 v[56:57], v227 offset:16896
	ds_read_b64 v[58:59], v228 offset:16896
	ds_read_b64 v[60:61], v227 offset:25344
	s_waitcnt lgkmcnt(14)
	ds_read_b64 v[62:63], v228 offset:25344
	s_waitcnt lgkmcnt(8)
	v_mfma_f32_16x16x32_bf16 v[140:143], v[64:67], v[174:177], v[140:143]
	v_mfma_f32_16x16x32_bf16 v[144:147], v[68:71], v[174:177], v[144:147]
	v_mfma_f32_16x16x32_bf16 v[148:151], v[72:75], v[174:177], v[148:151]
	v_mfma_f32_16x16x32_bf16 v[152:155], v[76:79], v[174:177], v[152:155]
	ds_read_b64 v[64:65], v227 offset:33792
	ds_read_b64 v[66:67], v228 offset:33792
	ds_read_b64 v[68:69], v227 offset:42240
	ds_read_b64 v[70:71], v228 offset:42240
	ds_read_b64 v[72:73], v227 offset:50688
	ds_read_b64 v[74:75], v228 offset:50688
	ds_read_b64 v[76:77], v227 offset:59136
	s_waitcnt lgkmcnt(14)
	ds_read_b64 v[78:79], v228 offset:59136
	s_waitcnt lgkmcnt(8)
	v_mfma_f32_16x16x32_bf16 v[124:127], v[48:51], v[178:181], v[124:127]
	v_mfma_f32_16x16x32_bf16 v[128:131], v[52:55], v[178:181], v[128:131]
	v_mfma_f32_16x16x32_bf16 v[132:135], v[56:59], v[178:181], v[132:135]
	v_mfma_f32_16x16x32_bf16 v[136:139], v[60:63], v[178:181], v[136:139]
	ds_read_b64 v[48:49], v234
	ds_read_b64 v[50:51], v234
	ds_read_b64 v[52:53], v234 offset:8448
	ds_read_b64 v[54:55], v234 offset:8448
	ds_read_b64 v[56:57], v234 offset:16896
	ds_read_b64 v[58:59], v234 offset:16896
	ds_read_b64 v[60:61], v234 offset:25344
	s_waitcnt lgkmcnt(14)
	ds_read_b64 v[62:63], v234 offset:25344
	s_waitcnt lgkmcnt(8)
	v_mfma_f32_16x16x32_bf16 v[140:143], v[64:67], v[178:181], v[140:143]
	v_mfma_f32_16x16x32_bf16 v[144:147], v[68:71], v[178:181], v[144:147]
	v_mfma_f32_16x16x32_bf16 v[148:151], v[72:75], v[178:181], v[148:151]
	v_mfma_f32_16x16x32_bf16 v[152:155], v[76:79], v[178:181], v[152:155]
	ds_read_b64 v[64:65], v234 offset:33792
	ds_read_b64 v[66:67], v234 offset:33792
	ds_read_b64 v[68:69], v234 offset:42240
	ds_read_b64 v[70:71], v234 offset:42240
	ds_read_b64 v[72:73], v234 offset:50688
	ds_read_b64 v[74:75], v234 offset:50688
	ds_read_b64 v[76:77], v234 offset:59136
	s_waitcnt lgkmcnt(14)
	ds_read_b64 v[78:79], v234 offset:59136
	v_div_scale_f32 v80, s[2:3], v81, v81, 1.0
	v_div_scale_f32 v83, vcc, 1.0, v81, 1.0
	v_rcp_f32_e32 v82, v80
	s_nop 0
	v_fma_f32 v164, -v80, v82, 1.0
	v_fmac_f32_e32 v82, v164, v82
	v_mul_f32_e32 v103, v83, v82
	v_fma_f32 v164, -v80, v103, v83
	v_fmac_f32_e32 v103, v164, v82
	v_fma_f32 v80, -v80, v103, v83
	v_div_fmas_f32 v80, v80, v82, v103
	v_div_fixup_f32 v80, v80, v81, 1.0
	s_waitcnt lgkmcnt(8)
	v_mfma_f32_16x16x32_bf16 v[124:127], v[48:51], v[198:201], v[124:127]
	v_mfma_f32_16x16x32_bf16 v[128:131], v[52:55], v[198:201], v[128:131]
	v_mfma_f32_16x16x32_bf16 v[132:135], v[56:59], v[198:201], v[132:135]
	v_mfma_f32_16x16x32_bf16 v[136:139], v[60:63], v[198:201], v[136:139]
	s_waitcnt lgkmcnt(0)
	v_mfma_f32_16x16x32_bf16 v[140:143], v[64:67], v[198:201], v[140:143]
	v_mfma_f32_16x16x32_bf16 v[144:147], v[68:71], v[198:201], v[144:147]
	v_mfma_f32_16x16x32_bf16 v[148:151], v[72:75], v[198:201], v[148:151]
	v_mfma_f32_16x16x32_bf16 v[152:155], v[76:79], v[198:201], v[152:155]
	s_movk_i32 s2, 0xc00
	v_mov_b64_e32 v[82:83], s[78:79]
	v_mad_u64_u32 v[82:83], s[0:1], v102, s2, v[82:83]
	v_mov_b32_e32 v164, v83
	v_mov_b32_e32 v165, v189
	v_mad_u64_u32 v[164:165], s[0:1], v100, s2, v[164:165]
	s_lshl_b32 s0, s80, 7
	v_mov_b32_e32 v83, v164
	s_ashr_i32 s1, s0, 31
	v_lshl_add_u64 v[82:83], s[0:1], 1, v[82:83]
	v_lshlrev_b32_e32 v188, 1, v88
	s_nop 1
	v_lshl_add_u64 v[82:83], v[82:83], 0, v[188:189]
	v_mul_f32_e32 v124, v80, v124
	v_mul_f32_e32 v125, v80, v125
	v_mul_f32_e32 v126, v80, v126
	v_mul_f32_e32 v127, v80, v127
	v_mul_f32_e32 v128, v80, v128
	v_mul_f32_e32 v129, v80, v129
	v_mul_f32_e32 v130, v80, v130
	v_mul_f32_e32 v131, v80, v131
	v_mul_f32_e32 v132, v80, v132
	v_mul_f32_e32 v133, v80, v133
	v_mul_f32_e32 v134, v80, v134
	v_mul_f32_e32 v135, v80, v135
	v_mul_f32_e32 v136, v80, v136
	v_mul_f32_e32 v137, v80, v137
	v_mul_f32_e32 v138, v80, v138
	v_mul_f32_e32 v139, v80, v139
	v_mul_f32_e32 v140, v80, v140
	v_mul_f32_e32 v141, v80, v141
	v_mul_f32_e32 v142, v80, v142
	v_mul_f32_e32 v143, v80, v143
	v_mul_f32_e32 v144, v80, v144
	v_mul_f32_e32 v145, v80, v145
	v_mul_f32_e32 v146, v80, v146
	v_mul_f32_e32 v147, v80, v147
	v_mul_f32_e32 v148, v80, v148
	v_mul_f32_e32 v149, v80, v149
	v_mul_f32_e32 v150, v80, v150
	v_mul_f32_e32 v151, v80, v151
	v_mul_f32_e32 v152, v80, v152
	v_mul_f32_e32 v153, v80, v153
	v_mul_f32_e32 v154, v80, v154
	v_mul_f32_e32 v155, v80, v155
	v_cvt_pk_bf16_f32 v48, v124, v125
	v_cvt_pk_bf16_f32 v49, v126, v127
	v_cvt_pk_bf16_f32 v50, v128, v129
	v_cvt_pk_bf16_f32 v51, v130, v131
	v_cvt_pk_bf16_f32 v52, v132, v133
	v_cvt_pk_bf16_f32 v53, v134, v135
	v_cvt_pk_bf16_f32 v54, v136, v137
	v_cvt_pk_bf16_f32 v55, v138, v139
	v_cvt_pk_bf16_f32 v56, v140, v141
	v_cvt_pk_bf16_f32 v57, v142, v143
	v_cvt_pk_bf16_f32 v58, v144, v145
	v_cvt_pk_bf16_f32 v59, v146, v147
	v_cvt_pk_bf16_f32 v60, v148, v149
	v_cvt_pk_bf16_f32 v61, v150, v151
	v_cvt_pk_bf16_f32 v62, v152, v153
	v_cvt_pk_bf16_f32 v63, v154, v155
	global_store_dwordx2 v[82:83], v[48:49], off
	global_store_dwordx2 v[82:83], v[50:51], off offset:32
	global_store_dwordx2 v[82:83], v[52:53], off offset:64
	global_store_dwordx2 v[82:83], v[54:55], off offset:96
	global_store_dwordx2 v[82:83], v[56:57], off offset:128
	global_store_dwordx2 v[82:83], v[58:59], off offset:160
	global_store_dwordx2 v[82:83], v[60:61], off offset:192
	global_store_dwordx2 v[82:83], v[62:63], off offset:224
	s_mov_b64 s[86:87], exec
	v_readlane_b32 s0, v255, 3
	v_readlane_b32 s1, v255, 4
	s_and_b64 s[0:1], s[86:87], s[0:1]
	s_mov_b64 exec, s[0:1]
	s_cbranch_execz .LBB0_652
	v_cmp_gt_f32_e32 vcc, s33, v81
	v_readlane_b32 s0, v253, 38
	v_readlane_b32 s1, v253, 39
	v_cndmask_b32_e64 v48, 0, 32, vcc
	v_ldexp_f32 v48, v81, v48
	v_log_f32_e32 v48, v48
	v_cndmask_b32_e32 v49, 0, v237, vcc
	s_ashr_i32 s81, s80, 31
	v_mul_f32_e32 v50, 0x3f317217, v48
	v_fma_f32 v50, v48, s93, -v50
	v_fmac_f32_e32 v50, 0x3377d1cf, v48
	v_fmac_f32_e32 v50, 0x3f317217, v48
	v_cmp_lt_f32_e64 vcc, |v48|, s92
	s_nop 1
	v_cndmask_b32_e32 v48, v48, v50, vcc
	v_sub_f32_e32 v48, v48, v49
	v_add_f32_e32 v52, v101, v48
	v_mad_u64_u32 v[48:49], s[0:1], v102, 48, s[0:1]
	v_mov_b32_e32 v50, v49
	v_mad_u64_u32 v[50:51], s[0:1], v100, 48, v[50:51]
	v_mov_b32_e32 v49, v50
	v_lshl_add_u64 v[48:49], s[80:81], 2, v[48:49]
	global_store_dword v[48:49], v52, off
	s_branch .LBB0_652
